# conv unit: LDS staging of the input window de-serialised (six loads in flight instead of a load/wait/write ladder)
# speedup vs baseline: 1.0133x; 1.0053x over previous
.LBB0_992:
	v_mbcnt_lo_u32_b32 v0, -1, 0
	v_mbcnt_hi_u32_b32 v0, -1, v0
	s_movk_i32 s10, 0xbc0
	v_add_u32_e32 v8, s33, v0
	s_nop 0
	v_cmp_gt_i32_e32 vcc, s10, v8
	s_and_saveexec_b64 s[10:11], vcc
	s_cbranch_execz .LBB0_997
	s_add_i32 s21, s19, -15
	v_lshrrev_b32_e32 v125, 5, v8
	v_lshlrev_b32_e32 v122, 3, v8
	v_and_b32_e32 v122, 0xf8, v122
	v_lshlrev_b32_e32 v122, 1, v122
	v_mov_b32_e32 v123, v153
	v_lshl_add_u32 v124, v125, 9, v122
	v_mov_b32_e32 v117, v153
	s_movk_i32 s14, 0x1c0
	v_cmp_gt_u32_e64 s[12:13], s14, v8
	v_mov_b32_e32 v92, 0
	v_mov_b32_e32 v93, 0
	v_mov_b32_e32 v94, 0
	v_mov_b32_e32 v95, 0
	v_mov_b32_e32 v116, v125
	v_add_u32_e32 v116, s21, v116
	v_cmp_gt_u32_e32 vcc, s20, v116
	s_and_saveexec_b64 s[14:15], vcc
	v_lshl_add_u64 v[118:119], s[8:9], 0, v[116:117]
	v_mov_b64_e32 v[120:121], s[70:71]
	v_mad_u64_u32 v[120:121], s[22:23], v118, s60, v[120:121]
	v_mov_b32_e32 v118, v121
	v_mad_u64_u32 v[118:119], s[22:23], v119, s60, v[118:119]
	v_mov_b32_e32 v121, v118
	v_lshl_add_u64 v[118:119], v[120:121], 0, v[122:123]
	v_add_co_u32_e32 v118, vcc, 0x1000, v118
	s_nop 1
	v_addc_co_u32_e32 v119, vcc, 0, v119, vcc
	global_load_dwordx4 v[92:95], v[118:119], off offset:1024
	s_or_b64 exec, exec, s[14:15]
	v_mov_b32_e32 v96, 0
	v_mov_b32_e32 v97, 0
	v_mov_b32_e32 v98, 0
	v_mov_b32_e32 v99, 0
	v_add_u32_e32 v116, 16, v125
	v_add_u32_e32 v116, s21, v116
	v_cmp_gt_u32_e32 vcc, s20, v116
	s_and_saveexec_b64 s[14:15], vcc
	v_lshl_add_u64 v[118:119], s[8:9], 0, v[116:117]
	v_mov_b64_e32 v[120:121], s[70:71]
	v_mad_u64_u32 v[120:121], s[22:23], v118, s60, v[120:121]
	v_mov_b32_e32 v118, v121
	v_mad_u64_u32 v[118:119], s[22:23], v119, s60, v[118:119]
	v_mov_b32_e32 v121, v118
	v_lshl_add_u64 v[118:119], v[120:121], 0, v[122:123]
	v_add_co_u32_e32 v118, vcc, 0x1000, v118
	s_nop 1
	v_addc_co_u32_e32 v119, vcc, 0, v119, vcc
	global_load_dwordx4 v[96:99], v[118:119], off offset:1024
	s_or_b64 exec, exec, s[14:15]
	v_mov_b32_e32 v100, 0
	v_mov_b32_e32 v101, 0
	v_mov_b32_e32 v102, 0
	v_mov_b32_e32 v103, 0
	v_add_u32_e32 v116, 32, v125
	v_add_u32_e32 v116, s21, v116
	v_cmp_gt_u32_e32 vcc, s20, v116
	s_and_saveexec_b64 s[14:15], vcc
	v_lshl_add_u64 v[118:119], s[8:9], 0, v[116:117]
	v_mov_b64_e32 v[120:121], s[70:71]
	v_mad_u64_u32 v[120:121], s[22:23], v118, s60, v[120:121]
	v_mov_b32_e32 v118, v121
	v_mad_u64_u32 v[118:119], s[22:23], v119, s60, v[118:119]
	v_mov_b32_e32 v121, v118
	v_lshl_add_u64 v[118:119], v[120:121], 0, v[122:123]
	v_add_co_u32_e32 v118, vcc, 0x1000, v118
	s_nop 1
	v_addc_co_u32_e32 v119, vcc, 0, v119, vcc
	global_load_dwordx4 v[100:103], v[118:119], off offset:1024
	s_or_b64 exec, exec, s[14:15]
	v_mov_b32_e32 v104, 0
	v_mov_b32_e32 v105, 0
	v_mov_b32_e32 v106, 0
	v_mov_b32_e32 v107, 0
	v_add_u32_e32 v116, 48, v125
	v_add_u32_e32 v116, s21, v116
	v_cmp_gt_u32_e32 vcc, s20, v116
	s_and_saveexec_b64 s[14:15], vcc
	v_lshl_add_u64 v[118:119], s[8:9], 0, v[116:117]
	v_mov_b64_e32 v[120:121], s[70:71]
	v_mad_u64_u32 v[120:121], s[22:23], v118, s60, v[120:121]
	v_mov_b32_e32 v118, v121
	v_mad_u64_u32 v[118:119], s[22:23], v119, s60, v[118:119]
	v_mov_b32_e32 v121, v118
	v_lshl_add_u64 v[118:119], v[120:121], 0, v[122:123]
	v_add_co_u32_e32 v118, vcc, 0x1000, v118
	s_nop 1
	v_addc_co_u32_e32 v119, vcc, 0, v119, vcc
	global_load_dwordx4 v[104:107], v[118:119], off offset:1024
	s_or_b64 exec, exec, s[14:15]
	v_mov_b32_e32 v108, 0
	v_mov_b32_e32 v109, 0
	v_mov_b32_e32 v110, 0
	v_mov_b32_e32 v111, 0
	v_add_u32_e32 v116, 64, v125
	v_add_u32_e32 v116, s21, v116
	v_cmp_gt_u32_e32 vcc, s20, v116
	s_and_saveexec_b64 s[14:15], vcc
	v_lshl_add_u64 v[118:119], s[8:9], 0, v[116:117]
	v_mov_b64_e32 v[120:121], s[70:71]
	v_mad_u64_u32 v[120:121], s[22:23], v118, s60, v[120:121]
	v_mov_b32_e32 v118, v121
	v_mad_u64_u32 v[118:119], s[22:23], v119, s60, v[118:119]
	v_mov_b32_e32 v121, v118
	v_lshl_add_u64 v[118:119], v[120:121], 0, v[122:123]
	v_add_co_u32_e32 v118, vcc, 0x1000, v118
	s_nop 1
	v_addc_co_u32_e32 v119, vcc, 0, v119, vcc
	global_load_dwordx4 v[108:111], v[118:119], off offset:1024
	s_or_b64 exec, exec, s[14:15]
	v_mov_b32_e32 v112, 0
	v_mov_b32_e32 v113, 0
	v_mov_b32_e32 v114, 0
	v_mov_b32_e32 v115, 0
	v_add_u32_e32 v116, 80, v125
	v_add_u32_e32 v116, s21, v116
	v_cmp_gt_u32_e32 vcc, s20, v116
	s_and_b64 vcc, vcc, s[12:13]
	s_and_saveexec_b64 s[14:15], vcc
	v_lshl_add_u64 v[118:119], s[8:9], 0, v[116:117]
	v_mov_b64_e32 v[120:121], s[70:71]
	v_mad_u64_u32 v[120:121], s[22:23], v118, s60, v[120:121]
	v_mov_b32_e32 v118, v121
	v_mad_u64_u32 v[118:119], s[22:23], v119, s60, v[118:119]
	v_mov_b32_e32 v121, v118
	v_lshl_add_u64 v[118:119], v[120:121], 0, v[122:123]
	v_add_co_u32_e32 v118, vcc, 0x1000, v118
	s_nop 1
	v_addc_co_u32_e32 v119, vcc, 0, v119, vcc
	global_load_dwordx4 v[112:115], v[118:119], off offset:1024
	s_or_b64 exec, exec, s[14:15]
	s_waitcnt vmcnt(5)
	ds_write_b128 v124, v[92:95]
	s_waitcnt vmcnt(4)
	ds_write_b128 v124, v[96:99] offset:8192
	s_waitcnt vmcnt(3)
	ds_write_b128 v124, v[100:103] offset:16384
	s_waitcnt vmcnt(2)
	ds_write_b128 v124, v[104:107] offset:24576
	s_waitcnt vmcnt(1)
	ds_write_b128 v124, v[108:111] offset:32768
	s_waitcnt vmcnt(0)
	s_and_saveexec_b64 s[14:15], s[12:13]
	ds_write_b128 v124, v[112:115] offset:40960
	s_or_b64 exec, exec, s[14:15]
